# quarter-unit K loop (four half-stage slots): refill phase split in two by one more barrier (five per K step)
# speedup vs baseline: 1.0015x; 1.0015x over previous
.Lq5_top:
	ds_read_b128 v[148:151], v214
	ds_read_b128 v[152:155], v214 offset:1024
	ds_read_b128 v[156:159], v214 offset:2048
	ds_read_b128 v[160:163], v214 offset:3072
	v_lshl_add_u64 v[2:3], s[34:35], 0, v[200:201]
	s_add_i32 m0, s48, 0xc000
	ds_read_b128 v[188:191], v216
	ds_read_b128 v[192:195], v216 offset:1024
	ds_read_b128 v[180:183], v216 offset:2048
	ds_read_b128 v[184:187], v216 offset:3072
	ds_read_b128 v[172:175], v216 offset:4096
	ds_read_b128 v[176:179], v216 offset:5120
	ds_read_b128 v[164:167], v216 offset:6144
	ds_read_b128 v[168:171], v216 offset:7168
	v_lshl_add_u64 v[2:3], s[34:35], 0, v[202:203]
	s_add_i32 m0, s48, 0xe000
	s_nop 0
	s_setprio 1
	v_mfma_f32_16x16x32_bf16 v[128:131], v[4:7], v[44:47], v[128:131]
	v_mfma_f32_16x16x32_bf16 v[124:127], v[12:15], v[44:47], v[124:127]
	v_mfma_f32_16x16x32_bf16 v[120:123], v[4:7], v[36:39], v[120:123]
	v_mfma_f32_16x16x32_bf16 v[116:119], v[12:15], v[36:39], v[116:119]
	v_mfma_f32_16x16x32_bf16 v[104:107], v[4:7], v[28:31], v[104:107]
	v_mfma_f32_16x16x32_bf16 v[100:103], v[12:15], v[28:31], v[100:103]
	s_setprio 0
	s_barrier
	v_cmp_ne_u32_e64 s[2:3], 1, v217
	s_andn2_b64 vcc, exec, s[26:27]
	s_add_u32 s56, s34, 0xfff80080
	s_addc_u32 s57, s35, -1
	s_cmp_eq_u32 s77, 10
	s_cselect_b32 s59, s39, s57
	s_cselect_b32 s58, s38, s56
	s_cselect_b32 s57, s47, s41
	s_cselect_b32 s56, s46, s18
	s_setprio 1
	v_mfma_f32_16x16x32_bf16 v[88:91], v[4:7], v[20:23], v[88:91]
	v_mfma_f32_16x16x32_bf16 v[84:87], v[12:15], v[20:23], v[84:87]
	v_mfma_f32_16x16x32_bf16 v[128:131], v[8:11], v[48:51], v[128:131]
	v_mfma_f32_16x16x32_bf16 v[124:127], v[16:19], v[48:51], v[124:127]
	v_mfma_f32_16x16x32_bf16 v[120:123], v[8:11], v[40:43], v[120:123]
	v_mfma_f32_16x16x32_bf16 v[116:119], v[16:19], v[40:43], v[116:119]
	s_setprio 0
	s_waitcnt lgkmcnt(0)
	s_barrier
	s_setprio 1
	v_mfma_f32_16x16x32_bf16 v[104:107], v[8:11], v[32:35], v[104:107]
	v_mfma_f32_16x16x32_bf16 v[100:103], v[16:19], v[32:35], v[100:103]
	v_mfma_f32_16x16x32_bf16 v[88:91], v[8:11], v[24:27], v[88:91]
	v_mfma_f32_16x16x32_bf16 v[84:87], v[16:19], v[24:27], v[84:87]
	s_setprio 0
	s_waitcnt vmcnt(8)
	s_barrier
	s_mov_b32 m0, s49
	v_lshl_add_u64 v[2:3], s[56:57], 0, v[198:199]
	s_add_u32 s78, s56, 0x80000
	global_load_lds_dwordx4 v[2:3], off
	v_lshl_add_u64 v[204:205], s[56:57], 0, v[196:197]
	s_mov_b32 m0, s50
	s_addc_u32 s79, s57, 0
	global_load_lds_dwordx4 v[204:205], off
	s_barrier
	v_lshl_add_u64 v[206:207], s[78:79], 0, v[198:199]
	s_mov_b32 m0, s51
	v_lshl_add_u64 v[208:209], s[58:59], 0, v[196:197]
	v_lshl_add_u64 v[206:207], s[78:79], 0, v[196:197]
	s_mov_b32 m0, s60
	s_and_b64 vcc, exec, s[2:3]
	v_lshl_add_u64 v[206:207], s[58:59], 0, v[198:199]
	s_mov_b32 m0, s48
	s_nop 0
	global_load_lds_dwordx4 v[206:207], off
	s_mov_b32 m0, s61
	s_nop 0
	global_load_lds_dwordx4 v[208:209], off
	s_barrier
	v_add_u32_e32 v1, 0x18000, v213
	ds_read_b128 v[4:7], v1
	ds_read_b128 v[8:11], v1 offset:1024
	ds_read_b128 v[12:15], v1 offset:2048
	ds_read_b128 v[16:19], v1 offset:3072
	v_add_u32_e32 v1, 0x1c000, v213
	s_add_u32 s58, s58, 0x80000
	s_addc_u32 s59, s59, 0
	s_mov_b32 m0, s62
	v_lshl_add_u64 v[218:219], s[58:59], 0, v[198:199]
	ds_read_b128 v[44:47], v216 offset:32768
	ds_read_b128 v[48:51], v216 offset:33792
	ds_read_b128 v[36:39], v216 offset:34816
	ds_read_b128 v[40:43], v216 offset:35840
	ds_read_b128 v[28:31], v216 offset:36864
	ds_read_b128 v[32:35], v216 offset:37888
	ds_read_b128 v[20:23], v216 offset:38912
	ds_read_b128 v[24:27], v216 offset:39936
	v_lshl_add_u64 v[218:219], s[58:59], 0, v[196:197]
	s_mov_b32 m0, s63
	s_nop 0
	s_setprio 1
	v_mfma_f32_16x16x32_bf16 v[128:131], v[148:151], v[188:191], v[128:131]
	v_mfma_f32_16x16x32_bf16 v[124:127], v[156:159], v[188:191], v[124:127]
	v_mfma_f32_16x16x32_bf16 v[120:123], v[148:151], v[180:183], v[120:123]
	v_mfma_f32_16x16x32_bf16 v[116:119], v[156:159], v[180:183], v[116:119]
	v_mfma_f32_16x16x32_bf16 v[104:107], v[148:151], v[172:175], v[104:107]
	v_mfma_f32_16x16x32_bf16 v[100:103], v[156:159], v[172:175], v[100:103]
	s_setprio 0
	s_barrier
	s_and_b64 vcc, exec, s[2:3]
	s_setprio 1
	v_mfma_f32_16x16x32_bf16 v[88:91], v[148:151], v[164:167], v[88:91]
	v_mfma_f32_16x16x32_bf16 v[84:87], v[156:159], v[164:167], v[84:87]
	v_mfma_f32_16x16x32_bf16 v[128:131], v[152:155], v[192:195], v[128:131]
	v_mfma_f32_16x16x32_bf16 v[124:127], v[160:163], v[192:195], v[124:127]
	v_mfma_f32_16x16x32_bf16 v[120:123], v[152:155], v[184:187], v[120:123]
	v_mfma_f32_16x16x32_bf16 v[116:119], v[160:163], v[184:187], v[116:119]
	s_setprio 0
	s_waitcnt lgkmcnt(0)
	s_barrier
	s_setprio 1
	v_mfma_f32_16x16x32_bf16 v[104:107], v[152:155], v[176:179], v[104:107]
	v_mfma_f32_16x16x32_bf16 v[100:103], v[160:163], v[176:179], v[100:103]
	v_mfma_f32_16x16x32_bf16 v[88:91], v[152:155], v[168:171], v[88:91]
	v_mfma_f32_16x16x32_bf16 v[84:87], v[160:163], v[168:171], v[84:87]
	s_setprio 0
	s_waitcnt vmcnt(8)
	s_barrier
	s_mov_b32 m0, s66
	v_lshl_add_u64 v[2:3], v[2:3], 0, s[16:17]
	s_add_u32 s56, s56, 0x80080
	global_load_lds_dwordx4 v[2:3], off
	v_lshl_add_u64 v[2:3], v[204:205], 0, s[16:17]
	s_mov_b32 m0, s67
	s_addc_u32 s57, s57, 0
	global_load_lds_dwordx4 v[2:3], off
	s_barrier
	v_lshl_add_u64 v[2:3], s[56:57], 0, v[198:199]
	s_mov_b32 m0, s70
	s_and_b64 vcc, exec, s[2:3]
	v_lshl_add_u64 v[2:3], s[56:57], 0, v[196:197]
	s_mov_b32 m0, s71
	s_nop 0
	v_lshl_add_u64 v[2:3], v[206:207], 0, s[16:17]
	s_mov_b32 m0, s68
	s_nop 0
	global_load_lds_dwordx4 v[2:3], off
	v_lshl_add_u64 v[2:3], v[208:209], 0, s[16:17]
	s_mov_b32 m0, s69
	s_nop 0
	global_load_lds_dwordx4 v[2:3], off
	s_barrier
	s_add_i32 s77, s77, 2
	s_add_u32 s34, s34, 0x100
	s_addc_u32 s35, s35, 0
	s_add_u32 s18, s18, 0x100
	s_addc_u32 s41, s41, 0
	s_cmp_gt_u32 s77, 13
	ds_read_b128 v[148:151], v215
	ds_read_b128 v[152:155], v215 offset:1024
	ds_read_b128 v[156:159], v215 offset:2048
	ds_read_b128 v[160:163], v215 offset:3072
	v_lshl_add_u64 v[2:3], s[34:35], 0, v[200:201]
	s_add_i32 m0, s48, 0xc000
	ds_read_b128 v[188:191], v216 offset:16384
	ds_read_b128 v[192:195], v216 offset:17408
	ds_read_b128 v[180:183], v216 offset:18432
	ds_read_b128 v[184:187], v216 offset:19456
	ds_read_b128 v[172:175], v216 offset:20480
	ds_read_b128 v[176:179], v216 offset:21504
	ds_read_b128 v[164:167], v216 offset:22528
	ds_read_b128 v[168:171], v216 offset:23552
	v_lshl_add_u64 v[2:3], s[34:35], 0, v[202:203]
	s_add_i32 m0, s48, 0xe000
	s_nop 0
	s_setprio 1
	v_mfma_f32_16x16x32_bf16 v[128:131], v[4:7], v[44:47], v[128:131]
	v_mfma_f32_16x16x32_bf16 v[124:127], v[12:15], v[44:47], v[124:127]
	v_mfma_f32_16x16x32_bf16 v[120:123], v[4:7], v[36:39], v[120:123]
	v_mfma_f32_16x16x32_bf16 v[116:119], v[12:15], v[36:39], v[116:119]
	v_mfma_f32_16x16x32_bf16 v[104:107], v[4:7], v[28:31], v[104:107]
	v_mfma_f32_16x16x32_bf16 v[100:103], v[12:15], v[28:31], v[100:103]
	s_setprio 0
	s_barrier
	v_cmp_ne_u32_e64 s[2:3], 1, v217
	s_andn2_b64 vcc, exec, s[26:27]
	s_add_u32 s56, s34, 0xfff80080
	s_addc_u32 s57, s35, -1
	s_cmp_eq_u32 s77, 12
	s_cselect_b32 s59, s39, s57
	s_cselect_b32 s58, s38, s56
	s_cselect_b32 s57, s47, s41
	s_cselect_b32 s56, s46, s18
	s_setprio 1
	v_mfma_f32_16x16x32_bf16 v[88:91], v[4:7], v[20:23], v[88:91]
	v_mfma_f32_16x16x32_bf16 v[84:87], v[12:15], v[20:23], v[84:87]
	v_mfma_f32_16x16x32_bf16 v[128:131], v[8:11], v[48:51], v[128:131]
	v_mfma_f32_16x16x32_bf16 v[124:127], v[16:19], v[48:51], v[124:127]
	v_mfma_f32_16x16x32_bf16 v[120:123], v[8:11], v[40:43], v[120:123]
	v_mfma_f32_16x16x32_bf16 v[116:119], v[16:19], v[40:43], v[116:119]
	s_setprio 0
	s_waitcnt lgkmcnt(0)
	s_barrier
	s_setprio 1
	v_mfma_f32_16x16x32_bf16 v[104:107], v[8:11], v[32:35], v[104:107]
	v_mfma_f32_16x16x32_bf16 v[100:103], v[16:19], v[32:35], v[100:103]
	v_mfma_f32_16x16x32_bf16 v[88:91], v[8:11], v[24:27], v[88:91]
	v_mfma_f32_16x16x32_bf16 v[84:87], v[16:19], v[24:27], v[84:87]
	s_setprio 0
	s_waitcnt vmcnt(8)
	s_barrier
	s_cmp_eq_u32 s77, 12
	s_cbranch_scc1 .Lq5_o_n0
	s_mov_b32 m0, s51
	v_lshl_add_u64 v[2:3], s[56:57], 0, v[198:199]
	s_add_u32 s78, s56, 0x80000
	global_load_lds_dwordx4 v[2:3], off
	v_lshl_add_u64 v[204:205], s[56:57], 0, v[196:197]
	s_mov_b32 m0, s60
	s_addc_u32 s79, s57, 0
	global_load_lds_dwordx4 v[204:205], off
.Lq5_o_n0:
	s_barrier
	s_cmp_eq_u32 s77, 12
	s_cbranch_scc1 .Lq5_o_m0
	v_lshl_add_u64 v[206:207], s[78:79], 0, v[198:199]
	s_mov_b32 m0, s66
	v_lshl_add_u64 v[208:209], s[58:59], 0, v[196:197]
	v_lshl_add_u64 v[206:207], s[78:79], 0, v[196:197]
	s_mov_b32 m0, s67
	s_and_b64 vcc, exec, s[2:3]
	v_lshl_add_u64 v[206:207], s[58:59], 0, v[198:199]
	s_mov_b32 m0, s62
	s_nop 0
	global_load_lds_dwordx4 v[206:207], off
	s_mov_b32 m0, s63
	s_nop 0
	global_load_lds_dwordx4 v[208:209], off

.Lq5_o_w:
	s_barrier
	s_cmp_eq_u32 s77, 12
	s_cbranch_scc1 .Lq5_o_n1
	s_mov_b32 m0, s70
	v_lshl_add_u64 v[2:3], v[2:3], 0, s[16:17]
	s_add_u32 s56, s56, 0x80080
	global_load_lds_dwordx4 v[2:3], off
	v_lshl_add_u64 v[2:3], v[204:205], 0, s[16:17]
	s_mov_b32 m0, s71
	s_addc_u32 s57, s57, 0
	global_load_lds_dwordx4 v[2:3], off
.Lq5_o_n1:
	s_barrier
	s_cmp_eq_u32 s77, 12
	s_cbranch_scc1 .Lq5_o_m1
	v_lshl_add_u64 v[2:3], s[56:57], 0, v[198:199]
	s_add_i32 m0, s48, 0x20000
	s_and_b64 vcc, exec, s[2:3]
	v_lshl_add_u64 v[2:3], s[56:57], 0, v[196:197]
	s_add_i32 m0, s48, 0x22000
	s_nop 0
	v_lshl_add_u64 v[2:3], v[206:207], 0, s[16:17]
	s_add_i32 m0, s48, 0xc000
	s_nop 0
	global_load_lds_dwordx4 v[2:3], off
	v_lshl_add_u64 v[2:3], v[208:209], 0, s[16:17]
	s_add_i32 m0, s48, 0xe000
	s_nop 0
	global_load_lds_dwordx4 v[2:3], off

.Lq6_top:
	ds_read_b128 v[180:183], v247
	ds_read_b128 v[184:187], v247 offset:1024
	ds_read_b128 v[188:191], v247 offset:2048
	ds_read_b128 v[192:195], v247 offset:3072
	v_lshl_add_u64 v[2:3], s[38:39], 0, v[232:233]
	s_add_i32 m0, s44, 0xc000
	ds_read_b128 v[220:223], v249
	ds_read_b128 v[224:227], v249 offset:1024
	ds_read_b128 v[212:215], v249 offset:2048
	ds_read_b128 v[216:219], v249 offset:3072
	ds_read_b128 v[204:207], v249 offset:4096
	ds_read_b128 v[208:211], v249 offset:5120
	ds_read_b128 v[196:199], v249 offset:6144
	ds_read_b128 v[200:203], v249 offset:7168
	v_lshl_add_u64 v[2:3], s[38:39], 0, v[234:235]
	s_add_i32 m0, s44, 0xe000
	s_nop 0
	s_setprio 1
	v_mfma_f32_16x16x32_bf16 v[68:71], v[4:7], v[44:47], v[160:163]
	v_mfma_f32_16x16x32_bf16 v[72:75], v[12:15], v[44:47], v[156:159]
	v_mfma_f32_16x16x32_bf16 v[76:79], v[4:7], v[36:39], v[152:155]
	v_mfma_f32_16x16x32_bf16 v[80:83], v[12:15], v[36:39], v[148:151]
	v_mfma_f32_16x16x32_bf16 v[84:87], v[4:7], v[28:31], v[136:139]
	v_mfma_f32_16x16x32_bf16 v[92:95], v[12:15], v[28:31], v[132:135]
	s_setprio 0
	s_barrier
	v_cmp_ne_u32_e64 s[4:5], 1, v251
	s_andn2_b64 vcc, exec, s[34:35]
	s_add_u32 s40, s38, 0xfff80080
	s_addc_u32 s41, s39, -1
	s_cmp_eq_u32 s84, 26
	s_cselect_b32 s47, s29, s41
	s_cselect_b32 s46, s28, s40
	s_cselect_b32 s41, s37, s27
	s_cselect_b32 s40, s36, s16
	s_setprio 1
	v_mfma_f32_16x16x32_bf16 v[96:99], v[4:7], v[20:23], v[120:123]
	v_mfma_f32_16x16x32_bf16 v[100:103], v[12:15], v[20:23], v[112:115]
	v_mfma_f32_16x16x32_bf16 v[68:71], v[8:11], v[48:51], v[68:71]
	v_mfma_f32_16x16x32_bf16 v[72:75], v[16:19], v[48:51], v[72:75]
	v_mfma_f32_16x16x32_bf16 v[76:79], v[8:11], v[40:43], v[76:79]
	v_mfma_f32_16x16x32_bf16 v[80:83], v[16:19], v[40:43], v[80:83]
	s_setprio 0
	s_waitcnt lgkmcnt(0)
	s_barrier
	s_setprio 1
	v_mfma_f32_16x16x32_bf16 v[84:87], v[8:11], v[32:35], v[84:87]
	v_mfma_f32_16x16x32_bf16 v[92:95], v[16:19], v[32:35], v[92:95]
	v_mfma_f32_16x16x32_bf16 v[96:99], v[8:11], v[24:27], v[96:99]
	v_mfma_f32_16x16x32_bf16 v[100:103], v[16:19], v[24:27], v[100:103]
	s_setprio 0
	s_waitcnt vmcnt(8)
	s_barrier
	s_mov_b32 m0, s45
	v_lshl_add_u64 v[2:3], s[40:41], 0, v[230:231]
	s_add_u32 s86, s40, 0x80000
	global_load_lds_dwordx4 v[2:3], off
	v_lshl_add_u64 v[236:237], s[40:41], 0, v[228:229]
	s_mov_b32 m0, s48
	s_addc_u32 s87, s41, 0
	global_load_lds_dwordx4 v[236:237], off
	s_barrier
	v_lshl_add_u64 v[54:55], s[86:87], 0, v[230:231]
	s_mov_b32 m0, s49
	v_lshl_add_u64 v[238:239], s[46:47], 0, v[230:231]
	v_lshl_add_u64 v[54:55], s[86:87], 0, v[228:229]
	s_mov_b32 m0, s50
	v_lshl_add_u64 v[240:241], s[46:47], 0, v[228:229]
	s_mov_b32 m0, s44
	s_and_b64 vcc, exec, s[4:5]
	global_load_lds_dwordx4 v[238:239], off
	s_mov_b32 m0, s51
	s_nop 0
	global_load_lds_dwordx4 v[240:241], off
	s_barrier
	v_add_u32_e32 v1, 0x18000, v246
	ds_read_b128 v[4:7], v1
	ds_read_b128 v[8:11], v1 offset:1024
	ds_read_b128 v[12:15], v1 offset:2048
	ds_read_b128 v[16:19], v1 offset:3072
	v_add_u32_e32 v1, 0x1c000, v246
	s_add_u32 s46, s46, 0x80000
	s_addc_u32 s47, s47, 0
	s_mov_b32 m0, s56
	v_lshl_add_u64 v[112:113], s[46:47], 0, v[230:231]
	ds_read_b128 v[44:47], v249 offset:32768
	ds_read_b128 v[48:51], v249 offset:33792
	ds_read_b128 v[36:39], v249 offset:34816
	ds_read_b128 v[40:43], v249 offset:35840
	ds_read_b128 v[28:31], v249 offset:36864
	ds_read_b128 v[32:35], v249 offset:37888
	ds_read_b128 v[20:23], v249 offset:38912
	ds_read_b128 v[24:27], v249 offset:39936
	v_lshl_add_u64 v[112:113], s[46:47], 0, v[228:229]
	s_mov_b32 m0, s57
	s_nop 0
	s_setprio 1
	v_mfma_f32_16x16x32_bf16 v[68:71], v[180:183], v[220:223], v[68:71]
	v_mfma_f32_16x16x32_bf16 v[160:163], v[184:187], v[224:227], v[68:71]
	v_mfma_f32_16x16x32_bf16 v[68:71], v[188:191], v[220:223], v[72:75]
	v_mfma_f32_16x16x32_bf16 v[156:159], v[192:195], v[224:227], v[68:71]
	v_mfma_f32_16x16x32_bf16 v[68:71], v[180:183], v[212:215], v[76:79]
	v_mfma_f32_16x16x32_bf16 v[152:155], v[184:187], v[216:219], v[68:71]
	s_setprio 0
	s_barrier
	s_and_b64 vcc, exec, s[4:5]
	s_setprio 1
	v_mfma_f32_16x16x32_bf16 v[68:71], v[188:191], v[212:215], v[80:83]
	v_mfma_f32_16x16x32_bf16 v[148:151], v[192:195], v[216:219], v[68:71]
	v_mfma_f32_16x16x32_bf16 v[68:71], v[180:183], v[204:207], v[84:87]
	v_mfma_f32_16x16x32_bf16 v[136:139], v[184:187], v[208:211], v[68:71]
	v_mfma_f32_16x16x32_bf16 v[68:71], v[188:191], v[204:207], v[92:95]
	v_mfma_f32_16x16x32_bf16 v[132:135], v[192:195], v[208:211], v[68:71]
	s_setprio 0
	s_waitcnt lgkmcnt(0)
	s_barrier
	s_setprio 1
	v_mfma_f32_16x16x32_bf16 v[68:71], v[180:183], v[196:199], v[96:99]
	v_mfma_f32_16x16x32_bf16 v[120:123], v[184:187], v[200:203], v[68:71]
	v_mfma_f32_16x16x32_bf16 v[68:71], v[188:191], v[196:199], v[100:103]
	v_mfma_f32_16x16x32_bf16 v[112:115], v[192:195], v[200:203], v[68:71]
	s_setprio 0
	s_waitcnt vmcnt(8)
	s_barrier
	s_mov_b32 m0, s61
	v_lshl_add_u64 v[2:3], v[2:3], 0, s[14:15]
	s_add_u32 s40, s40, 0x80080
	global_load_lds_dwordx4 v[2:3], off
	v_lshl_add_u64 v[2:3], v[236:237], 0, s[14:15]
	s_mov_b32 m0, s62
	s_addc_u32 s41, s41, 0
	global_load_lds_dwordx4 v[2:3], off
	s_barrier
	v_lshl_add_u64 v[2:3], s[40:41], 0, v[230:231]
	s_mov_b32 m0, s65
	s_and_b64 vcc, exec, s[4:5]
	v_lshl_add_u64 v[2:3], s[40:41], 0, v[228:229]
	s_mov_b32 m0, s66
	s_nop 0
	v_lshl_add_u64 v[2:3], v[238:239], 0, s[14:15]
	s_mov_b32 m0, s63
	s_nop 0
	global_load_lds_dwordx4 v[2:3], off
	v_lshl_add_u64 v[2:3], v[240:241], 0, s[14:15]
	s_mov_b32 m0, s64
	s_nop 0
	global_load_lds_dwordx4 v[2:3], off
	s_barrier
	s_add_i32 s84, s84, 2
	s_add_u32 s38, s38, 0x100
	s_addc_u32 s39, s39, 0
	s_add_u32 s16, s16, 0x100
	s_addc_u32 s27, s27, 0
	s_cmp_gt_u32 s84, 29
	ds_read_b128 v[180:183], v248
	ds_read_b128 v[184:187], v248 offset:1024
	ds_read_b128 v[188:191], v248 offset:2048
	ds_read_b128 v[192:195], v248 offset:3072
	v_lshl_add_u64 v[2:3], s[38:39], 0, v[232:233]
	s_add_i32 m0, s44, 0xc000
	ds_read_b128 v[220:223], v249 offset:16384
	ds_read_b128 v[224:227], v249 offset:17408
	ds_read_b128 v[212:215], v249 offset:18432
	ds_read_b128 v[216:219], v249 offset:19456
	ds_read_b128 v[204:207], v249 offset:20480
	ds_read_b128 v[208:211], v249 offset:21504
	ds_read_b128 v[196:199], v249 offset:22528
	ds_read_b128 v[200:203], v249 offset:23552
	v_lshl_add_u64 v[2:3], s[38:39], 0, v[234:235]
	s_add_i32 m0, s44, 0xe000
	s_nop 0
	s_setprio 1
	v_mfma_f32_16x16x32_bf16 v[68:71], v[4:7], v[44:47], v[160:163]
	v_mfma_f32_16x16x32_bf16 v[72:75], v[12:15], v[44:47], v[156:159]
	v_mfma_f32_16x16x32_bf16 v[76:79], v[4:7], v[36:39], v[152:155]
	v_mfma_f32_16x16x32_bf16 v[80:83], v[12:15], v[36:39], v[148:151]
	v_mfma_f32_16x16x32_bf16 v[84:87], v[4:7], v[28:31], v[136:139]
	v_mfma_f32_16x16x32_bf16 v[92:95], v[12:15], v[28:31], v[132:135]
	s_setprio 0
	s_barrier
	v_cmp_ne_u32_e64 s[4:5], 1, v251
	s_andn2_b64 vcc, exec, s[34:35]
	s_add_u32 s40, s38, 0xfff80080
	s_addc_u32 s41, s39, -1
	s_cmp_eq_u32 s84, 28
	s_cselect_b32 s47, s29, s41
	s_cselect_b32 s46, s28, s40
	s_cselect_b32 s41, s37, s27
	s_cselect_b32 s40, s36, s16
	s_setprio 1
	v_mfma_f32_16x16x32_bf16 v[96:99], v[4:7], v[20:23], v[120:123]
	v_mfma_f32_16x16x32_bf16 v[100:103], v[12:15], v[20:23], v[112:115]
	v_mfma_f32_16x16x32_bf16 v[68:71], v[8:11], v[48:51], v[68:71]
	v_mfma_f32_16x16x32_bf16 v[72:75], v[16:19], v[48:51], v[72:75]
	v_mfma_f32_16x16x32_bf16 v[76:79], v[8:11], v[40:43], v[76:79]
	v_mfma_f32_16x16x32_bf16 v[80:83], v[16:19], v[40:43], v[80:83]
	s_setprio 0
	s_waitcnt lgkmcnt(0)
	s_barrier
	s_setprio 1
	v_mfma_f32_16x16x32_bf16 v[84:87], v[8:11], v[32:35], v[84:87]
	v_mfma_f32_16x16x32_bf16 v[92:95], v[16:19], v[32:35], v[92:95]
	v_mfma_f32_16x16x32_bf16 v[96:99], v[8:11], v[24:27], v[96:99]
	v_mfma_f32_16x16x32_bf16 v[100:103], v[16:19], v[24:27], v[100:103]
	s_setprio 0
	s_waitcnt vmcnt(8)
	s_barrier
	s_cmp_eq_u32 s84, 28
	s_cbranch_scc1 .Lq6_o_n0
	s_mov_b32 m0, s49
	v_lshl_add_u64 v[2:3], s[40:41], 0, v[230:231]
	s_add_u32 s86, s40, 0x80000
	global_load_lds_dwordx4 v[2:3], off
	v_lshl_add_u64 v[236:237], s[40:41], 0, v[228:229]
	s_mov_b32 m0, s50
	s_addc_u32 s87, s41, 0
	global_load_lds_dwordx4 v[236:237], off
.Lq6_o_n0:
	s_barrier
	s_cmp_eq_u32 s84, 28
	s_cbranch_scc1 .Lq6_o_m0
	v_lshl_add_u64 v[54:55], s[86:87], 0, v[230:231]
	s_mov_b32 m0, s61
	v_lshl_add_u64 v[238:239], s[46:47], 0, v[230:231]
	v_lshl_add_u64 v[54:55], s[86:87], 0, v[228:229]
	s_mov_b32 m0, s62
	v_lshl_add_u64 v[240:241], s[46:47], 0, v[228:229]
	s_mov_b32 m0, s56
	s_and_b64 vcc, exec, s[4:5]
	global_load_lds_dwordx4 v[238:239], off
	s_mov_b32 m0, s57
	s_nop 0
	global_load_lds_dwordx4 v[240:241], off

.Lq6_o_w:
	s_barrier
	s_cmp_eq_u32 s84, 28
	s_cbranch_scc1 .Lq6_o_n1
	s_mov_b32 m0, s65
	v_lshl_add_u64 v[2:3], v[2:3], 0, s[14:15]
	s_add_u32 s40, s40, 0x80080
	global_load_lds_dwordx4 v[2:3], off
	v_lshl_add_u64 v[2:3], v[236:237], 0, s[14:15]
	s_mov_b32 m0, s66
	s_addc_u32 s41, s41, 0
	global_load_lds_dwordx4 v[2:3], off
.Lq6_o_n1:
	s_barrier
	s_cmp_eq_u32 s84, 28
	s_cbranch_scc1 .Lq6_o_m1
	v_lshl_add_u64 v[2:3], s[40:41], 0, v[230:231]
	s_add_i32 m0, s44, 0x20000
	s_and_b64 vcc, exec, s[4:5]
	v_lshl_add_u64 v[2:3], s[40:41], 0, v[228:229]
	s_add_i32 m0, s44, 0x22000
	s_nop 0
	v_lshl_add_u64 v[2:3], v[238:239], 0, s[14:15]
	s_add_i32 m0, s44, 0xc000
	s_nop 0
	global_load_lds_dwordx4 v[2:3], off
	v_lshl_add_u64 v[2:3], v[240:241], 0, s[14:15]
	s_add_i32 m0, s44, 0xe000
	s_nop 0
	global_load_lds_dwordx4 v[2:3], off
